# P9 row pass: the 15 serialized bf16 piece loads of a non-tail row issued together (one wait), on top of v60
# speedup vs baseline: 1.0077x; 1.0077x over previous
.LBB0_1002:
	v_cndmask_b32_e64 v70, 0, 1, s[16:17]
	v_cmp_ne_u32_e64 s[0:1], 1, v70
	s_andn2_b64 vcc, exec, s[16:17]
	s_mov_b64 s[16:17], -1
	s_cbranch_vccnz .LBB0_1032
	v_add_co_u32_e32 v70, vcc, 0xce001000, v132
	s_nop 1
	v_addc_co_u32_e32 v71, vcc, -1, v133, vcc
	global_load_dwordx2 v[72:73], v[70:71], off offset:-3584 nt
	v_add_co_u32_e32 v74, vcc, 0xce001000, v132
	s_nop 1
	v_addc_co_u32_e32 v75, vcc, -1, v133, vcc
	global_load_dwordx2 v[76:77], v[74:75], off offset:-3072 nt
	v_add_co_u32_e32 v78, vcc, 0xce001000, v132
	s_nop 1
	v_addc_co_u32_e32 v79, vcc, -1, v133, vcc
	global_load_dwordx2 v[80:81], v[78:79], off offset:-2560 nt
	v_add_co_u32_e32 v82, vcc, 0xce001000, v132
	s_nop 1
	v_addc_co_u32_e32 v83, vcc, -1, v133, vcc
	global_load_dwordx2 v[84:85], v[82:83], off offset:-2048 nt
	v_add_co_u32_e32 v86, vcc, 0xce001000, v132
	s_nop 1
	v_addc_co_u32_e32 v87, vcc, -1, v133, vcc
	global_load_dwordx2 v[88:89], v[86:87], off offset:-1536 nt
	v_add_co_u32_e32 v90, vcc, 0xce001000, v132
	s_nop 1
	v_addc_co_u32_e32 v91, vcc, -1, v133, vcc
	global_load_dwordx2 v[92:93], v[90:91], off offset:-1024 nt
	v_add_co_u32_e32 v94, vcc, 0xce001000, v132
	s_nop 1
	v_addc_co_u32_e32 v95, vcc, -1, v133, vcc
	global_load_dwordx2 v[96:97], v[94:95], off offset:-512 nt
	v_add_co_u32_e32 v98, vcc, 0xce001000, v132
	s_nop 1
	v_addc_co_u32_e32 v99, vcc, -1, v133, vcc
	global_load_dwordx2 v[100:101], v[98:99], off nt
	v_add_co_u32_e32 v102, vcc, 0xce002000, v132
	s_nop 1
	v_addc_co_u32_e32 v103, vcc, -1, v133, vcc
	global_load_dwordx2 v[104:105], v[102:103], off offset:-3584 nt
	v_add_co_u32_e32 v106, vcc, 0xce002000, v132
	s_nop 1
	v_addc_co_u32_e32 v107, vcc, -1, v133, vcc
	global_load_dwordx2 v[108:109], v[106:107], off offset:-3072 nt
	v_add_co_u32_e32 v110, vcc, 0xce002000, v132
	s_nop 1
	v_addc_co_u32_e32 v111, vcc, -1, v133, vcc
	global_load_dwordx2 v[112:113], v[110:111], off offset:-2560 nt
	v_add_co_u32_e32 v114, vcc, 0xce002000, v132
	s_nop 1
	v_addc_co_u32_e32 v115, vcc, -1, v133, vcc
	global_load_dwordx2 v[116:117], v[114:115], off offset:-2048 nt
	v_add_co_u32_e32 v118, vcc, 0xce002000, v132
	s_nop 1
	v_addc_co_u32_e32 v119, vcc, -1, v133, vcc
	global_load_dwordx2 v[120:121], v[118:119], off offset:-1536 nt
	v_add_co_u32_e32 v122, vcc, 0xce002000, v132
	s_nop 1
	v_addc_co_u32_e32 v123, vcc, -1, v133, vcc
	global_load_dwordx2 v[124:125], v[122:123], off offset:-1024 nt
	v_add_co_u32_e32 v126, vcc, 0xce002000, v132
	s_nop 1
	v_addc_co_u32_e32 v127, vcc, -1, v133, vcc
	global_load_dwordx2 v[128:129], v[126:127], off offset:-512 nt
	s_waitcnt vmcnt(0)
	v_lshlrev_b32_e32 v70, 16, v72
	v_and_b32_e32 v71, 0xffff0000, v72
	v_lshlrev_b32_e32 v72, 16, v73
	v_and_b32_e32 v73, 0xffff0000, v73
	v_lshlrev_b32_e32 v74, 16, v76
	v_and_b32_e32 v75, 0xffff0000, v76
	v_lshlrev_b32_e32 v76, 16, v77
	v_and_b32_e32 v77, 0xffff0000, v77
	v_lshlrev_b32_e32 v78, 16, v80
	v_and_b32_e32 v79, 0xffff0000, v80
	v_lshlrev_b32_e32 v80, 16, v81
	v_and_b32_e32 v81, 0xffff0000, v81
	v_lshlrev_b32_e32 v82, 16, v84
	v_and_b32_e32 v83, 0xffff0000, v84
	v_lshlrev_b32_e32 v84, 16, v85
	v_and_b32_e32 v85, 0xffff0000, v85
	v_lshlrev_b32_e32 v86, 16, v88
	v_and_b32_e32 v87, 0xffff0000, v88
	v_lshlrev_b32_e32 v88, 16, v89
	v_and_b32_e32 v89, 0xffff0000, v89
	v_lshlrev_b32_e32 v90, 16, v92
	v_and_b32_e32 v91, 0xffff0000, v92
	v_lshlrev_b32_e32 v92, 16, v93
	v_and_b32_e32 v93, 0xffff0000, v93
	v_lshlrev_b32_e32 v94, 16, v96
	v_and_b32_e32 v95, 0xffff0000, v96
	v_lshlrev_b32_e32 v96, 16, v97
	v_and_b32_e32 v97, 0xffff0000, v97
	v_lshlrev_b32_e32 v98, 16, v100
	v_and_b32_e32 v99, 0xffff0000, v100
	v_lshlrev_b32_e32 v100, 16, v101
	v_and_b32_e32 v101, 0xffff0000, v101
	v_lshlrev_b32_e32 v102, 16, v104
	v_and_b32_e32 v103, 0xffff0000, v104
	v_lshlrev_b32_e32 v104, 16, v105
	v_and_b32_e32 v105, 0xffff0000, v105
	v_lshlrev_b32_e32 v106, 16, v108
	v_and_b32_e32 v107, 0xffff0000, v108
	v_lshlrev_b32_e32 v108, 16, v109
	v_and_b32_e32 v109, 0xffff0000, v109
	v_lshlrev_b32_e32 v110, 16, v112
	v_and_b32_e32 v111, 0xffff0000, v112
	v_lshlrev_b32_e32 v112, 16, v113
	v_and_b32_e32 v113, 0xffff0000, v113
	v_lshlrev_b32_e32 v114, 16, v116
	v_and_b32_e32 v115, 0xffff0000, v116
	v_lshlrev_b32_e32 v116, 16, v117
	v_and_b32_e32 v117, 0xffff0000, v117
	v_lshlrev_b32_e32 v118, 16, v120
	v_and_b32_e32 v119, 0xffff0000, v120
	v_lshlrev_b32_e32 v120, 16, v121
	v_and_b32_e32 v121, 0xffff0000, v121
	v_lshlrev_b32_e32 v122, 16, v124
	v_and_b32_e32 v123, 0xffff0000, v124
	v_lshlrev_b32_e32 v124, 16, v125
	v_and_b32_e32 v125, 0xffff0000, v125
	v_lshlrev_b32_e32 v126, 16, v128
	v_and_b32_e32 v127, 0xffff0000, v128
	v_lshlrev_b32_e32 v128, 16, v129
	v_and_b32_e32 v129, 0xffff0000, v129
	s_branch .LBB0_997
	v_add_co_u32_e32 v70, vcc, 0xce001000, v132
	s_nop 1
	v_addc_co_u32_e32 v71, vcc, -1, v133, vcc
	global_load_dwordx2 v[72:73], v[70:71], off offset:-3584 nt
	s_waitcnt vmcnt(0)
	v_lshlrev_b32_e32 v70, 16, v72
	v_and_b32_e32 v71, 0xffff0000, v72
	v_lshlrev_b32_e32 v72, 16, v73
	v_and_b32_e32 v73, 0xffff0000, v73
	s_cbranch_execz .LBB0_1033
